# stagger-24 stack + every in-proj store write-through and no leader L2 write-back at the in-proj barrier either (fence elision at norm and in-proj barriers)
# baseline (speedup 1.0000x reference)
; __device__ __forceinline__ unsigned xb_add(unsigned* p, unsigned v) { return __hip_atomic_fetch_add(p, v, __ATOMIC_RELAXED, __HIP_MEMORY_SCOPE_AGENT); }
; __device__ __forceinline__ void xcd_barrier(const XcdBarrier& b) {
;     asm volatile("s_waitcnt vmcnt(0)" ::: "memory");
;     __syncthreads();
;     if (threadIdx.x == 0) {
;         unsigned* bar = b.bar;
;         __builtin_amdgcn_s_waitcnt(0);
;         unsigned nloc = b.st[0], nx = b.st[1];
;         if (nloc == 0u) { xcd_barrier_complete(bar, b.x, nloc, nx); b.st[0] = nloc; b.st[1] = nx; }
;         const unsigned old = xb_add(&bar[XB_XSUB(b.x)], 1u);
;         const unsigned gen = old / nloc;
;         if (old + 1u == (gen + 1u) * nloc) {
;             __builtin_amdgcn_fence(__ATOMIC_RELEASE, "agent");
;             asm volatile("s_waitcnt vmcnt(0)" ::: "memory");
;             const unsigned og = xb_add(&bar[XB_TOP], 1u);
;             const unsigned tg = og / nx;
;             if (og + 1u == (tg + 1u) * nx) xb_add(&bar[XB_TOPGEN], 1u);
.LBB0_386:
	s_getreg_b32 s2, hwreg(HW_REG_XCC_ID, 0, 4)
	s_waitcnt vmcnt(0)
	v_writelane_b32 v255, s0, 13
	s_waitcnt vmcnt(0)
	s_barrier
	v_writelane_b32 v255, s1, 14
	s_mov_b64 s[0:1], exec
	v_readlane_b32 s4, v253, 2
	v_readlane_b32 s5, v253, 3
	s_and_b64 s[4:5], s[0:1], s[4:5]
	s_mov_b64 exec, s[4:5]
	s_cbranch_execz .LBB0_439
	v_mov_b32_e32 v0, 0x20020
	s_waitcnt vmcnt(0) lgkmcnt(0)
	ds_read2_b32 v[2:3], v0 offset1:1
	s_and_b32 s3, s2, 15
	s_lshl_b32 s3, s3, 8
	s_add_u32 s6, s78, 0x1701400
	s_addc_u32 s7, s79, 0
	s_add_u32 s6, s6, s3
	s_addc_u32 s7, s7, 0
	s_add_u32 s8, s6, 0x1000
	s_addc_u32 s9, s7, 0
	s_add_u32 s10, s78, 0x1703400
	s_addc_u32 s11, s79, 0
	s_waitcnt lgkmcnt(0)
	v_readfirstlane_b32 s30, v2
	v_readfirstlane_b32 s31, v3
	s_nop 3
	s_cmp_eq_u32 s30, 0
	s_cbranch_scc1 .Lxb_slow_i
	s_lshl_b32 s29, s66, 2
	s_add_i32 s29, s29, 2
	global_atomic_add v2, v173, v212, s[6:7] sc0
	buffer_inv sc1
	s_add_i32 s32, s29, 1
	s_mul_i32 s5, s32, s30
	s_mul_i32 s32, s32, s31
	s_waitcnt vmcnt(1)
	v_readfirstlane_b32 s3, v2
	s_nop 3
	s_add_i32 s3, s3, 1
	s_cmp_lg_u32 s3, s5
	s_cbranch_scc1 .Lxb_local_i
	global_atomic_add v173, v212, s[10:11]
	s_mov_b32 s3, 0
